# combo10 + static first mixer ticket per workgroup (ticket = blockIdx; counter tickets offset by 256) to avoid 256 simultaneous pops after the grid barrier
# speedup vs baseline: 1.0030x; 1.0030x over previous
; #define LAS __attribute__((address_space(3)))
; __device__ __forceinline__ int opaque_tid() { int t; asm volatile("v_mov_b32 %0, %1" : "=v"(t) : "v"((int)threadIdx.x)); return t; }
; __global__ void __launch_bounds__(NTHREADS, 2) mega_fwd(Params P) {
;     ...
;         {
;             LAS int* qslot = (LAS int*)(ldsl + RING_BYTES + 1024);
;             const int n_gqa = 384, n_na = 384, n_sg = 132, n_cx = lastl ? 0 : 24;
;             const int n_prod = n_gqa + n_na + n_sg + n_cx;
;             const int ntot = n_prod + 256 + (lastl ? 0 : 24);
;             unsigned* cw = ctl + CW_DEP + (size_t)l * 66 * 16;
;             for (;;) {
;                 if (opaque_tid() == 0) qslot[0] = (int)atomicAdd(ctl + 64 * (l + 1), 1u);
.LBB0_437:
	s_or_b64 exec, exec, s[34:35]
	v_readlane_b32 s0, v252, 11
	v_readlane_b32 s1, v252, 12
	s_and_b64 s[0:1], s[0:1], exec
	s_cselect_b32 s0, 24, 0
	s_or_b32 s1, s0, 0x384
	v_writelane_b32 v252, s1, 15
	s_lshl_b32 s0, s0, 1
	s_or_b32 s52, s0, 0x484
	s_mov_b64 s[0:1], s[76:77]
	v_readlane_b32 s20, v252, 9
	s_waitcnt lgkmcnt(0)
	s_barrier
	s_mul_i32 s3, s20, 0x1080
	s_mul_hi_u32 s2, s20, 0x1080
	s_add_u32 s0, s0, s3
	s_addc_u32 s1, s1, s2
	v_readlane_b32 s21, v252, 10
	s_add_u32 s53, s0, 0x8000
	s_addc_u32 s54, s1, 0
	s_lshl_b64 s[0:1], s[20:21], 21
	v_writelane_b32 v252, s0, 16
	s_lshl_b32 s86, s20, 8
	v_readlane_b32 s4, v253, 25
	v_writelane_b32 v252, s1, 17
	s_lshl_b64 s[0:1], s[20:21], 17
	s_lshl_b64 s[2:3], s[86:87], 2
	v_readlane_b32 s8, v253, 29
	v_readlane_b32 s9, v253, 30
	s_add_u32 s2, s8, s2
	s_addc_u32 s3, s9, s3
	v_writelane_b32 v252, s2, 18
	v_readlane_b32 s6, v253, 27
	v_readlane_b32 s7, v253, 28
	v_writelane_b32 v252, s3, 19
	v_readlane_b32 s2, v254, 10
	s_add_u32 s0, s2, s0
	v_writelane_b32 v252, s0, 20
	v_readlane_b32 s0, v254, 11
	s_addc_u32 s0, s0, s1
	v_readlane_b32 s5, v253, 26
	v_writelane_b32 v252, s0, 21
	s_lshl_b64 s[0:1], s[20:21], 11
	s_add_u32 s0, s6, s0
	v_writelane_b32 v252, s0, 22
	s_addc_u32 s0, s7, s1
	v_writelane_b32 v252, s0, 23
	v_writelane_b32 v252, s52, 24
	v_writelane_b32 v252, s53, 25
	v_readlane_b32 s10, v253, 31
	v_readlane_b32 s11, v253, 32
	v_readlane_b32 s12, v253, 33
	v_readlane_b32 s13, v253, 34
	v_readlane_b32 s14, v253, 35
	v_readlane_b32 s15, v253, 36
	v_readlane_b32 s16, v253, 37
	v_readlane_b32 s17, v253, 38
	v_readlane_b32 s18, v253, 39
	v_readlane_b32 s19, v253, 40
	v_writelane_b32 v252, s54, 26
	s_mov_b32 s101, 0
	v_readlane_b32 s100, v254, 57
	s_nop 3
	s_sub_i32 s100, s100, 0x100
	v_mov_b32_e32 v0, s100
	s_mov_b32 s101, 1
	s_branch .LBB0_441

; __device__ __forceinline__ int opaque_tid() { int t; asm volatile("v_mov_b32 %0, %1" : "=v"(t) : "v"((int)threadIdx.x)); return t; }
; __global__ void __launch_bounds__(NTHREADS, 2) mega_fwd(Params P) {
;     ...
;                 if (opaque_tid() == 0) qslot[0] = (int)atomicAdd(ctl + 64 * (l + 1), 1u);
;                 __syncthreads();
;                 const int idx = __builtin_amdgcn_readfirstlane(qslot[0]);
;                 __syncthreads();
.Lpop_have:
	v_add_u32_e32 v0, 0x100, v0
	v_readlane_b32 s2, v254, 42
	s_nop 1
	v_mov_b32_e32 v2, s2
	s_waitcnt lgkmcnt(0)
	ds_write_b32 v2, v0
